# v30 + DFT stage 2 gate rows and results staged through a wave-private LDS block: 4 row-contiguous dwordx4 loads / stores replace 8 scattered dwordx2 each
# speedup vs baseline: 1.0144x; 1.0024x over previous
.LBB0_114:
	s_cbranch_execz .LBB0_111
	v_readlane_b32 s2, v247, 39
	v_readlane_b32 s3, v247, 40
	s_andn2_b64 vcc, exec, s[2:3]
	s_cbranch_vccnz .LBB0_118
	v_lshrrev_b32_e32 v1, 5, v201
	v_lshl_or_b32 v2, s23, 1, v1
	v_and_b32_e32 v1, 15, v200
	v_lshl_or_b32 v4, s23, 4, v1
	v_ashrrev_i32_e32 v5, 31, v4
	v_readlane_b32 s8, v245, 20
	v_lshrrev_b32_e32 v1, 2, v200
	v_lshlrev_b64 v[6:7], 9, v[4:5]
	v_readlane_b32 s9, v245, 21
	v_and_b32_e32 v8, 12, v1
	v_lshlrev_b32_e32 v154, 1, v8
	v_lshl_add_u64 v[6:7], s[8:9], 0, v[6:7]
	v_lshrrev_b32_e32 v1, 2, v201
	v_lshlrev_b32_e32 v3, 3, v201
	s_and_b64 s[2:3], s[76:77], exec
	v_lshl_add_u64 v[6:7], v[6:7], 0, v[154:155]
	s_mov_b64 s[8:9], 0x2aa0000
	v_mul_u32_u24_e32 v1, 0x120, v1
	v_and_b32_e32 v3, 24, v3
	v_lshl_add_u64 v[34:35], v[6:7], 0, s[8:9]
	s_cselect_b32 s8, 4, 6
	v_add3_u32 v91, 0, v1, v3
	v_ashrrev_i32_e32 v3, 31, v2
	v_lshlrev_b64 v[36:37], s8, v[4:5]
	v_lshlrev_b64 v[38:39], 11, v[2:3]
	s_mov_b64 s[8:9], 0x8000
	v_lshl_add_u64 v[40:41], v[38:39], 0, s[8:9]
	s_mov_b64 s[8:9], 0x10000
	v_lshl_add_u64 v[42:43], v[38:39], 0, s[8:9]
	s_mov_b64 s[8:9], 0x18000
	v_lshl_add_u64 v[44:45], v[38:39], 0, s[8:9]
	s_mov_b64 s[8:9], 0x20000
	v_lshl_add_u64 v[46:47], v[38:39], 0, s[8:9]
	s_mov_b64 s[8:9], 0x28000
	v_lshl_add_u64 v[48:49], v[38:39], 0, s[8:9]
	s_mov_b64 s[8:9], 0x30000
	v_lshl_add_u64 v[50:51], v[38:39], 0, s[8:9]
	s_mov_b64 s[8:9], 0x38000
	v_lshl_add_u64 v[52:53], v[38:39], 0, s[8:9]
	s_mov_b64 s[8:9], 0x40000
	v_lshl_add_u64 v[54:55], v[38:39], 0, s[8:9]
	s_mov_b64 s[8:9], 0x48000
	v_lshl_add_u64 v[56:57], v[38:39], 0, s[8:9]
	s_mov_b64 s[8:9], 0x50000
	v_lshl_add_u64 v[58:59], v[38:39], 0, s[8:9]
	s_mov_b64 s[8:9], 0x58000
	v_lshl_add_u64 v[60:61], v[38:39], 0, s[8:9]
	s_mov_b64 s[8:9], 0x60000
	v_lshl_add_u64 v[62:63], v[38:39], 0, s[8:9]
	s_mov_b64 s[8:9], 0x68000
	v_lshl_add_u64 v[64:65], v[38:39], 0, s[8:9]
	s_mov_b64 s[8:9], 0x70000
	v_lshl_add_u64 v[66:67], v[38:39], 0, s[8:9]
	s_mov_b64 s[8:9], 0x78000
	s_cselect_b32 s2, 16, 64
	v_lshl_add_u64 v[68:69], v[38:39], 0, s[8:9]
	s_movk_i32 s8, 0x120
	v_mul_lo_u32 v100, v2, s8
	v_cvt_f32_ubyte0_e32 v2, s2
	v_rcp_iflag_f32_e32 v2, v2
	v_lshlrev_b32_e32 v0, 2, v200
	s_cselect_b32 s3, 11, 13
	s_sub_i32 s8, 0, s2
	v_mul_f32_e32 v2, 0x4f7ffffe, v2
	v_cvt_u32_f32_e32 v2, v2
	v_and_b32_e32 v0, 0x7c, v0
	v_cndmask_b32_e64 v32, v187, v198, s[76:77]
	v_lshl_add_u32 v90, v0, 1, 0
	v_readfirstlane_b32 s9, v2
	s_mul_i32 s8, s8, s9
	v_add_u32_e32 v1, 0x1200, v100
	s_mul_hi_u32 s8, s9, s8
	v_add_u32_e32 v92, 0x10e00, v91
	v_add_u32_e32 v93, 0x10e20, v91
	v_add_u32_e32 v94, 0x10e40, v91
	v_add_u32_e32 v95, 0x10e60, v91
	v_add_u32_e32 v96, 0x10e80, v91
	v_add_u32_e32 v97, 0x10ea0, v91
	v_add_u32_e32 v98, 0x10ec0, v91
	v_add_u32_e32 v99, 0x10ee0, v91
	v_mov_b32_e32 v33, v32
	s_add_i32 s13, s9, s8
	v_lshlrev_b32_e32 v154, 1, v0
	v_add_u32_e32 v101, v90, v1
	v_lshlrev_b32_e32 v70, 1, v8
	v_readlane_b32 s18, v246, 62
	s_mov_b32 s22, s47
	s_mul_i32 s100, s2, 0x2880
	v_lshrrev_b32_e32 v184, 4, v199
	v_mul_lo_u32 v184, v184, s100
	v_and_b32_e32 v185, 15, v199
	v_lshl_add_u32 v184, v185, 4, v184
	s_lshl_b32 s100, s100, 2
	v_lshrrev_b32_e32 v186, 4, v199
	v_mul_u32_u24_e32 v186, 0x120, v186
	v_lshl_add_u32 v185, v185, 4, v186
	s_mul_i32 s101, s23, 0x1200
	s_add_i32 s101, s101, 0x12000
	v_add_u32_e32 v185, s101, v185
	v_and_b32_e32 v186, 15, v199
	v_mul_u32_u24_e32 v186, 0x120, v186
	v_lshrrev_b32_e32 v196, 4, v199
	v_lshl_add_u32 v186, v196, 3, v186
	v_add_u32_e32 v186, s101, v186
	s_mul_i32 s101, s2, 0x1080
	v_lshrrev_b32_e32 v197, 4, v199
	v_mul_lo_u32 v197, v197, s101
	v_and_b32_e32 v196, 15, v199
	v_lshl_add_u32 v197, v196, 4, v197
	s_lshl_b32 s101, s101, 2
	global_load_dwordx2 v[238:239], v[34:35], off
	global_load_dwordx2 v[240:241], v[34:35], off offset:32
	global_load_dwordx2 v[234:235], v[34:35], off offset:64
	global_load_dwordx2 v[236:237], v[34:35], off offset:96
	global_load_dwordx2 v[230:231], v[34:35], off offset:128
	global_load_dwordx2 v[232:233], v[34:35], off offset:160
	global_load_dwordx2 v[226:227], v[34:35], off offset:192
	global_load_dwordx2 v[228:229], v[34:35], off offset:224
	global_load_dwordx2 v[222:223], v[34:35], off offset:256
	global_load_dwordx2 v[224:225], v[34:35], off offset:288
	global_load_dwordx2 v[218:219], v[34:35], off offset:320
	global_load_dwordx2 v[220:221], v[34:35], off offset:352
	global_load_dwordx2 v[214:215], v[34:35], off offset:384
	global_load_dwordx2 v[216:217], v[34:35], off offset:416
	global_load_dwordx2 v[210:211], v[34:35], off offset:448
	global_load_dwordx2 v[212:213], v[34:35], off offset:480
.LBB0_117:
	s_ashr_i32 s8, s22, 3
	s_abs_i32 s10, s8
	s_mul_hi_u32 s11, s10, s13
	s_mul_i32 s14, s11, s2
	s_sub_i32 s10, s10, s14
	s_ashr_i32 s9, s22, 31
	s_add_i32 s14, s11, 1
	s_sub_i32 s15, s10, s2
	s_cmp_ge_u32 s10, s2
	s_cselect_b32 s11, s14, s11
	s_cselect_b32 s10, s15, s10
	s_add_i32 s14, s11, 1
	s_cmp_ge_u32 s10, s2
	s_cselect_b32 s10, s14, s11
	s_xor_b32 s10, s10, s9
	s_sub_i32 s10, s10, s9
	s_mul_i32 s9, s10, s2
	s_sub_i32 s14, s8, s9
	s_mulk_i32 s8, 0x101
	s_ashr_i32 s9, s8, 31
	s_lshl_b64 s[8:9], s[8:9], 11
	s_add_u32 s11, s4, s8
	s_addc_u32 s15, s5, s9
	s_and_b32 s8, s18, 0x380
	s_lshl_b32 s8, s8, 1
	s_add_u32 s24, s11, s8
	s_addc_u32 s25, s15, 0
	v_lshl_add_u64 v[0:1], s[24:25], 0, v[154:155]
	v_lshl_add_u64 v[2:3], v[0:1], 0, v[38:39]
	global_load_dwordx2 v[72:73], v[2:3], off
	v_lshl_add_u64 v[2:3], v[0:1], 0, v[40:41]
	global_load_dwordx2 v[74:75], v[2:3], off
	v_lshl_add_u64 v[2:3], v[0:1], 0, v[42:43]
	global_load_dwordx2 v[76:77], v[2:3], off
	v_lshl_add_u64 v[2:3], v[0:1], 0, v[44:45]
	global_load_dwordx2 v[78:79], v[2:3], off
	v_lshl_add_u64 v[2:3], v[0:1], 0, v[46:47]
	global_load_dwordx2 v[80:81], v[2:3], off
	v_lshl_add_u64 v[2:3], v[0:1], 0, v[48:49]
	global_load_dwordx2 v[82:83], v[2:3], off
	v_lshl_add_u64 v[2:3], v[0:1], 0, v[50:51]
	global_load_dwordx2 v[84:85], v[2:3], off
	v_lshl_add_u64 v[2:3], v[0:1], 0, v[52:53]
	global_load_dwordx2 v[86:87], v[2:3], off
	v_lshl_add_u64 v[2:3], v[0:1], 0, v[54:55]
	global_load_dwordx2 v[88:89], v[2:3], off
	v_lshl_add_u64 v[2:3], v[0:1], 0, v[56:57]
	global_load_dwordx2 v[102:103], v[2:3], off
	v_lshl_add_u64 v[2:3], v[0:1], 0, v[58:59]
	global_load_dwordx2 v[104:105], v[2:3], off
	v_lshl_add_u64 v[2:3], v[0:1], 0, v[60:61]
	global_load_dwordx2 v[106:107], v[2:3], off
	v_lshl_add_u64 v[2:3], v[0:1], 0, v[62:63]
	global_load_dwordx2 v[108:109], v[2:3], off
	v_lshl_add_u64 v[2:3], v[0:1], 0, v[64:65]
	global_load_dwordx2 v[110:111], v[2:3], off
	v_lshl_add_u64 v[2:3], v[0:1], 0, v[66:67]
	global_load_dwordx2 v[112:113], v[2:3], off
	v_lshl_add_u64 v[0:1], v[0:1], 0, v[68:69]
	global_load_dwordx2 v[114:115], v[0:1], off
	s_ashr_i32 s11, s10, 31
	s_lshl_b64 s[10:11], s[10:11], s3
	s_ashr_i32 s15, s14, 31
	s_add_u32 s10, s10, s14
	v_add_u32_e32 v71, v90, v100
	s_addc_u32 s11, s11, s15
	s_mov_b32 s9, s96
	s_waitcnt vmcnt(14)
	ds_write2st64_b64 v71, v[72:73], v[74:75] offset1:9
	s_waitcnt vmcnt(12)
	ds_write2st64_b64 v71, v[76:77], v[78:79] offset0:18 offset1:27
	s_waitcnt vmcnt(10)
	ds_write2st64_b64 v71, v[80:81], v[82:83] offset0:36 offset1:45
	s_waitcnt vmcnt(8)
	ds_write2st64_b64 v71, v[84:85], v[86:87] offset0:54 offset1:63
	s_waitcnt vmcnt(6)
	ds_write2st64_b64 v71, v[88:89], v[102:103] offset0:72 offset1:81
	s_waitcnt vmcnt(4)
	ds_write2st64_b64 v71, v[104:105], v[106:107] offset0:90 offset1:99
	s_waitcnt vmcnt(2)
	ds_write2st64_b64 v71, v[108:109], v[110:111] offset0:108 offset1:117
	s_waitcnt vmcnt(1)
	ds_write_b64 v71, v[112:113] offset:64512
	s_waitcnt vmcnt(0)
	ds_write_b64 v101, v[114:115] offset:64512
	v_lshl_add_u64 v[72:73], s[10:11], 0, v[36:37]
	v_mov_b64_e32 v[74:75], s[92:93]
	v_mad_u64_u32 v[74:75], s[10:11], v72, s33, v[74:75]
	v_mad_i32_i24 v75, v73, s33, v75
	v_lshl_add_u64 v[74:75], v[74:75], 0, s[8:9]
	v_mov_b32_e32 v71, v155
	v_lshl_add_u64 v[74:75], v[74:75], 0, v[70:71]
	v_lshl_add_u64 v[102:103], v[74:75], 0, s[72:73]
	v_add_co_u32_e32 v74, vcc, s69, v74
	s_waitcnt lgkmcnt(0)
	s_nop 0
	v_addc_co_u32_e32 v75, vcc, 0, v75, vcc
	s_nop 0
	v_readfirstlane_b32 s98, v74
	v_readfirstlane_b32 s99, v75
	s_nop 4
	global_load_dwordx4 v[74:77], v184, s[98:99]
	s_add_u32 s98, s98, s100
	s_addc_u32 s99, s99, 0
	global_load_dwordx4 v[78:81], v184, s[98:99]
	s_add_u32 s98, s98, s100
	s_addc_u32 s99, s99, 0
	global_load_dwordx4 v[82:85], v184, s[98:99]
	s_add_u32 s98, s98, s100
	s_addc_u32 s99, s99, 0
	global_load_dwordx4 v[86:89], v184, s[98:99]
	s_barrier
	ds_read_b64_tr_b16 v[104:105], v91 offset:4608
	ds_read_b64_tr_b16 v[102:103], v91
	ds_read_b64_tr_b16 v[106:107], v91 offset:32
	ds_read_b64_tr_b16 v[108:109], v91 offset:4640
	ds_read_b64_tr_b16 v[110:111], v91 offset:64
	ds_read_b64_tr_b16 v[112:113], v91 offset:4672
	ds_read_b64_tr_b16 v[114:115], v91 offset:96
	ds_read_b64_tr_b16 v[116:117], v91 offset:4704
	ds_read_b64_tr_b16 v[118:119], v91 offset:128
	ds_read_b64_tr_b16 v[120:121], v91 offset:4736
	ds_read_b64_tr_b16 v[122:123], v91 offset:160
	ds_read_b64_tr_b16 v[124:125], v91 offset:4768
	ds_read_b64_tr_b16 v[126:127], v91 offset:192
	ds_read_b64_tr_b16 v[128:129], v91 offset:4800
	ds_read_b64_tr_b16 v[130:131], v91 offset:224
	ds_read_b64_tr_b16 v[132:133], v91 offset:4832
	ds_read_b64_tr_b16 v[134:135], v91 offset:9216
	ds_read_b64_tr_b16 v[136:137], v91 offset:13824
	ds_read_b64_tr_b16 v[138:139], v91 offset:9248
	ds_read_b64_tr_b16 v[140:141], v91 offset:13856
	ds_read_b64_tr_b16 v[142:143], v91 offset:9280
	ds_read_b64_tr_b16 v[144:145], v91 offset:13888
	ds_read_b64_tr_b16 v[146:147], v91 offset:9312
	ds_read_b64_tr_b16 v[148:149], v91 offset:13920
	ds_read_b64_tr_b16 v[156:157], v91 offset:9344
	ds_read_b64_tr_b16 v[158:159], v91 offset:13952
	ds_read_b64_tr_b16 v[160:161], v91 offset:9376
	ds_read_b64_tr_b16 v[162:163], v91 offset:13984
	ds_read_b64_tr_b16 v[164:165], v91 offset:9408
	ds_read_b64_tr_b16 v[166:167], v91 offset:14016
	ds_read_b64_tr_b16 v[168:169], v91 offset:9440
	ds_read_b64_tr_b16 v[170:171], v91 offset:14048
	s_waitcnt vmcnt(22) lgkmcnt(14)
	v_mfma_f32_16x16x32_bf16 v[102:105], v[102:105], v[238:241], 0
	v_mfma_f32_16x16x32_bf16 v[106:109], v[106:109], v[238:241], 0
	v_mfma_f32_16x16x32_bf16 v[110:113], v[110:113], v[238:241], 0
	v_mfma_f32_16x16x32_bf16 v[114:117], v[114:117], v[238:241], 0
	v_mfma_f32_16x16x32_bf16 v[118:121], v[118:121], v[238:241], 0
	v_mfma_f32_16x16x32_bf16 v[122:125], v[122:125], v[238:241], 0
	v_mfma_f32_16x16x32_bf16 v[126:129], v[126:129], v[238:241], 0
	v_mfma_f32_16x16x32_bf16 v[28:31], v[130:133], v[238:241], 0
	ds_read_b64_tr_b16 v[130:131], v91 offset:18432
	ds_read_b64_tr_b16 v[172:173], v91 offset:18464
	ds_read_b64_tr_b16 v[176:177], v91 offset:18496
	ds_read_b64_tr_b16 v[180:181], v91 offset:18528
	ds_read_b64_tr_b16 v[132:133], v91 offset:23040
	ds_read_b64_tr_b16 v[174:175], v91 offset:23072
	ds_read_b64_tr_b16 v[178:179], v91 offset:23104
	ds_read_b64_tr_b16 v[182:183], v91 offset:23136
	ds_read_b64_tr_b16 v[188:189], v91 offset:18560
	ds_read_b64_tr_b16 v[192:193], v91 offset:18592
	ds_read_b64_tr_b16 v[202:203], v91 offset:18624
	ds_read_b64_tr_b16 v[206:207], v91 offset:18656
	ds_read_b64_tr_b16 v[190:191], v91 offset:23168
	ds_read_b64_tr_b16 v[194:195], v91 offset:23200
	ds_read_b64_tr_b16 v[204:205], v91 offset:23232
	ds_read_b64_tr_b16 v[208:209], v91 offset:23264
	s_waitcnt vmcnt(20)
	v_mfma_f32_16x16x32_bf16 v[102:105], v[134:137], v[234:237], v[102:105]
	s_waitcnt lgkmcnt(14)
	v_mfma_f32_16x16x32_bf16 v[106:109], v[138:141], v[234:237], v[106:109]
	v_mfma_f32_16x16x32_bf16 v[110:113], v[142:145], v[234:237], v[110:113]
	v_mfma_f32_16x16x32_bf16 v[114:117], v[146:149], v[234:237], v[114:117]
	v_mfma_f32_16x16x32_bf16 v[118:121], v[156:159], v[234:237], v[118:121]
	v_mfma_f32_16x16x32_bf16 v[122:125], v[160:163], v[234:237], v[122:125]
	v_mfma_f32_16x16x32_bf16 v[126:129], v[164:167], v[234:237], v[126:129]
	v_mfma_f32_16x16x32_bf16 v[24:27], v[168:171], v[234:237], v[28:31]
	s_nop 2
	ds_read_b64_tr_b16 v[28:29], v91 offset:27648
	ds_read_b64_tr_b16 v[134:135], v91 offset:27680
	ds_read_b64_tr_b16 v[138:139], v91 offset:27712
	ds_read_b64_tr_b16 v[142:143], v91 offset:27744
	ds_read_b64_tr_b16 v[30:31], v91 offset:32256
	ds_read_b64_tr_b16 v[136:137], v91 offset:32288
	ds_read_b64_tr_b16 v[140:141], v91 offset:32320
	ds_read_b64_tr_b16 v[144:145], v91 offset:32352
	ds_read_b64_tr_b16 v[146:147], v91 offset:27776
	ds_read_b64_tr_b16 v[156:157], v91 offset:27808
	ds_read_b64_tr_b16 v[160:161], v91 offset:27840
	ds_read_b64_tr_b16 v[164:165], v91 offset:27872
	ds_read_b64_tr_b16 v[148:149], v91 offset:32384
	ds_read_b64_tr_b16 v[158:159], v91 offset:32416
	ds_read_b64_tr_b16 v[162:163], v91 offset:32448
	ds_read_b64_tr_b16 v[166:167], v91 offset:32480
	s_waitcnt vmcnt(18) lgkmcnt(14)
	v_mfma_f32_16x16x32_bf16 v[102:105], v[130:133], v[230:233], v[102:105]
	v_mfma_f32_16x16x32_bf16 v[106:109], v[172:175], v[230:233], v[106:109]
	v_mfma_f32_16x16x32_bf16 v[110:113], v[176:179], v[230:233], v[110:113]
	v_mfma_f32_16x16x32_bf16 v[114:117], v[180:183], v[230:233], v[114:117]
	v_mfma_f32_16x16x32_bf16 v[118:121], v[188:191], v[230:233], v[118:121]
	v_mfma_f32_16x16x32_bf16 v[122:125], v[192:195], v[230:233], v[122:125]
	v_mfma_f32_16x16x32_bf16 v[126:129], v[202:205], v[230:233], v[126:129]
	v_mfma_f32_16x16x32_bf16 v[20:23], v[206:209], v[230:233], v[24:27]
	s_nop 2
	ds_read_b64_tr_b16 v[24:25], v91 offset:36864
	ds_read_b64_tr_b16 v[130:131], v91 offset:36896
	ds_read_b64_tr_b16 v[168:169], v91 offset:36928
	ds_read_b64_tr_b16 v[172:173], v91 offset:36960
	ds_read_b64_tr_b16 v[26:27], v91 offset:41472
	ds_read_b64_tr_b16 v[132:133], v91 offset:41504
	ds_read_b64_tr_b16 v[170:171], v91 offset:41536
	ds_read_b64_tr_b16 v[174:175], v91 offset:41568
	ds_read_b64_tr_b16 v[176:177], v91 offset:36992
	ds_read_b64_tr_b16 v[180:181], v91 offset:37024
	ds_read_b64_tr_b16 v[188:189], v91 offset:37056
	ds_read_b64_tr_b16 v[192:193], v91 offset:37088
	ds_read_b64_tr_b16 v[178:179], v91 offset:41600
	ds_read_b64_tr_b16 v[182:183], v91 offset:41632
	ds_read_b64_tr_b16 v[190:191], v91 offset:41664
	ds_read_b64_tr_b16 v[194:195], v91 offset:41696
	s_waitcnt vmcnt(16) lgkmcnt(14)
	v_mfma_f32_16x16x32_bf16 v[28:31], v[28:31], v[226:229], v[102:105]
	v_mfma_f32_16x16x32_bf16 v[102:105], v[134:137], v[226:229], v[106:109]
	v_mfma_f32_16x16x32_bf16 v[106:109], v[138:141], v[226:229], v[110:113]
	v_mfma_f32_16x16x32_bf16 v[110:113], v[142:145], v[226:229], v[114:117]
	v_mfma_f32_16x16x32_bf16 v[114:117], v[146:149], v[226:229], v[118:121]
	v_mfma_f32_16x16x32_bf16 v[118:121], v[156:159], v[226:229], v[122:125]
	v_mfma_f32_16x16x32_bf16 v[122:125], v[160:163], v[226:229], v[126:129]
	v_mfma_f32_16x16x32_bf16 v[16:19], v[164:167], v[226:229], v[20:23]
	s_nop 2
	ds_read_b64_tr_b16 v[20:21], v91 offset:46080
	ds_read_b64_tr_b16 v[126:127], v91 offset:46112
	ds_read_b64_tr_b16 v[134:135], v91 offset:46144
	ds_read_b64_tr_b16 v[138:139], v91 offset:46176
	ds_read_b64_tr_b16 v[22:23], v91 offset:50688
	ds_read_b64_tr_b16 v[128:129], v91 offset:50720
	ds_read_b64_tr_b16 v[136:137], v91 offset:50752
	ds_read_b64_tr_b16 v[140:141], v91 offset:50784
	ds_read_b64_tr_b16 v[142:143], v91 offset:46208
	ds_read_b64_tr_b16 v[146:147], v91 offset:46240
	ds_read_b64_tr_b16 v[156:157], v91 offset:46272
	ds_read_b64_tr_b16 v[160:161], v91 offset:46304
	ds_read_b64_tr_b16 v[144:145], v91 offset:50816
	ds_read_b64_tr_b16 v[148:149], v91 offset:50848
	ds_read_b64_tr_b16 v[158:159], v91 offset:50880
	ds_read_b64_tr_b16 v[162:163], v91 offset:50912
	s_waitcnt vmcnt(14) lgkmcnt(14)
	v_mfma_f32_16x16x32_bf16 v[24:27], v[24:27], v[222:225], v[28:31]
	v_mfma_f32_16x16x32_bf16 v[28:31], v[130:133], v[222:225], v[102:105]
	v_mfma_f32_16x16x32_bf16 v[102:105], v[168:171], v[222:225], v[106:109]
	v_mfma_f32_16x16x32_bf16 v[106:109], v[172:175], v[222:225], v[110:113]
	v_mfma_f32_16x16x32_bf16 v[110:113], v[176:179], v[222:225], v[114:117]
	v_mfma_f32_16x16x32_bf16 v[114:117], v[180:183], v[222:225], v[118:121]
	v_mfma_f32_16x16x32_bf16 v[118:121], v[188:191], v[222:225], v[122:125]
	v_mfma_f32_16x16x32_bf16 v[12:15], v[192:195], v[222:225], v[16:19]
	s_nop 2
	ds_read_b64_tr_b16 v[16:17], v91 offset:55296
	ds_read_b64_tr_b16 v[122:123], v91 offset:55328
	ds_read_b64_tr_b16 v[130:131], v91 offset:55360
	ds_read_b64_tr_b16 v[164:165], v91 offset:55392
	ds_read_b64_tr_b16 v[18:19], v91 offset:59904
	ds_read_b64_tr_b16 v[124:125], v91 offset:59936
	ds_read_b64_tr_b16 v[132:133], v91 offset:59968
	ds_read_b64_tr_b16 v[166:167], v91 offset:60000
	ds_read_b64_tr_b16 v[168:169], v91 offset:55424
	ds_read_b64_tr_b16 v[172:173], v91 offset:55456
	ds_read_b64_tr_b16 v[176:177], v91 offset:55488
	ds_read_b64_tr_b16 v[180:181], v91 offset:55520
	ds_read_b64_tr_b16 v[170:171], v91 offset:60032
	ds_read_b64_tr_b16 v[174:175], v91 offset:60064
	ds_read_b64_tr_b16 v[178:179], v91 offset:60096
	ds_read_b64_tr_b16 v[182:183], v91 offset:60128
	s_waitcnt vmcnt(12) lgkmcnt(14)
	v_mfma_f32_16x16x32_bf16 v[20:23], v[20:23], v[218:221], v[24:27]
	v_mfma_f32_16x16x32_bf16 v[24:27], v[126:129], v[218:221], v[28:31]
	v_mfma_f32_16x16x32_bf16 v[28:31], v[134:137], v[218:221], v[102:105]
	v_mfma_f32_16x16x32_bf16 v[102:105], v[138:141], v[218:221], v[106:109]
	v_mfma_f32_16x16x32_bf16 v[106:109], v[142:145], v[218:221], v[110:113]
	v_mfma_f32_16x16x32_bf16 v[110:113], v[146:149], v[218:221], v[114:117]
	v_mfma_f32_16x16x32_bf16 v[114:117], v[156:159], v[218:221], v[118:121]
	v_mfma_f32_16x16x32_bf16 v[8:11], v[160:163], v[218:221], v[12:15]
	s_nop 2
	ds_read_b64_tr_b16 v[12:13], v91 offset:64512
	ds_read_b64_tr_b16 v[118:119], v91 offset:64544
	ds_read_b64_tr_b16 v[126:127], v91 offset:64576
	ds_read_b64_tr_b16 v[134:135], v91 offset:64608
	ds_read_b64_tr_b16 v[14:15], v92
	ds_read_b64_tr_b16 v[120:121], v93
	ds_read_b64_tr_b16 v[128:129], v94
	ds_read_b64_tr_b16 v[136:137], v95
	ds_read_b64_tr_b16 v[138:139], v91 offset:64640
	ds_read_b64_tr_b16 v[142:143], v91 offset:64672
	ds_read_b64_tr_b16 v[146:147], v91 offset:64704
	ds_read_b64_tr_b16 v[156:157], v91 offset:64736
	ds_read_b64_tr_b16 v[140:141], v96
	ds_read_b64_tr_b16 v[144:145], v97
	ds_read_b64_tr_b16 v[148:149], v98
	ds_read_b64_tr_b16 v[158:159], v99
	s_waitcnt vmcnt(10) lgkmcnt(14)
	v_mfma_f32_16x16x32_bf16 v[16:19], v[16:19], v[214:217], v[20:23]
	v_mfma_f32_16x16x32_bf16 v[20:23], v[122:125], v[214:217], v[24:27]
	v_mfma_f32_16x16x32_bf16 v[24:27], v[130:133], v[214:217], v[28:31]
	v_mfma_f32_16x16x32_bf16 v[28:31], v[164:167], v[214:217], v[102:105]
	v_mfma_f32_16x16x32_bf16 v[102:105], v[168:171], v[214:217], v[106:109]
	v_mfma_f32_16x16x32_bf16 v[106:109], v[172:175], v[214:217], v[110:113]
	v_mfma_f32_16x16x32_bf16 v[110:113], v[176:179], v[214:217], v[114:117]
	v_mfma_f32_16x16x32_bf16 v[4:7], v[180:183], v[214:217], v[8:11]
	s_waitcnt vmcnt(8) lgkmcnt(11)
	v_mfma_f32_16x16x32_bf16 v[8:11], v[12:15], v[210:213], v[16:19]
	s_waitcnt lgkmcnt(10)
	v_mfma_f32_16x16x32_bf16 v[12:15], v[118:121], v[210:213], v[20:23]
	s_waitcnt lgkmcnt(9)
	v_mfma_f32_16x16x32_bf16 v[16:19], v[126:129], v[210:213], v[24:27]
	s_waitcnt lgkmcnt(8)
	v_mfma_f32_16x16x32_bf16 v[20:23], v[134:137], v[210:213], v[28:31]
	s_waitcnt lgkmcnt(3)
	v_mfma_f32_16x16x32_bf16 v[24:27], v[138:141], v[210:213], v[102:105]
	s_waitcnt lgkmcnt(2)
	v_mfma_f32_16x16x32_bf16 v[28:31], v[142:145], v[210:213], v[106:109]
	s_waitcnt lgkmcnt(1)
	v_mfma_f32_16x16x32_bf16 v[102:105], v[146:149], v[210:213], v[110:113]
	s_waitcnt lgkmcnt(0)
	v_mfma_f32_16x16x32_bf16 v[0:3], v[156:159], v[210:213], v[4:7]
	s_nop 2
	s_waitcnt vmcnt(0)
	ds_write_b128 v185, v[74:77]
	ds_write_b128 v185, v[78:81] offset:1152
	ds_write_b128 v185, v[82:85] offset:2304
	ds_write_b128 v185, v[86:89] offset:3456
	s_waitcnt lgkmcnt(0)
	ds_read_b64 v[88:89], v186
	ds_read_b64 v[86:87], v186 offset:32
	ds_read_b64 v[84:85], v186 offset:64
	ds_read_b64 v[82:83], v186 offset:96
	ds_read_b64 v[80:81], v186 offset:128
	ds_read_b64 v[78:79], v186 offset:160
	ds_read_b64 v[76:77], v186 offset:192
	ds_read_b64 v[74:75], v186 offset:224
	s_waitcnt lgkmcnt(0)
	v_mov_b64_e32 v[4:5], s[38:39]
	v_mad_u64_u32 v[4:5], s[10:11], v72, s34, v[4:5]
	v_pk_mul_f32 v[6:7], v[32:33], v[8:9]
	s_waitcnt vmcnt(7)
	v_lshlrev_b32_e32 v8, 16, v88
	v_and_b32_e32 v9, 0xffff0000, v88
	v_mad_i32_i24 v5, v73, s34, v5
	v_pk_mul_f32 v[6:7], v[6:7], v[8:9]
	v_pk_mul_f32 v[8:9], v[32:33], v[10:11]
	v_lshlrev_b32_e32 v10, 16, v89
	v_and_b32_e32 v11, 0xffff0000, v89
	v_lshl_add_u64 v[4:5], v[4:5], 0, s[8:9]
	v_pk_mul_f32 v[8:9], v[8:9], v[10:11]
	v_lshl_add_u64 v[4:5], v[4:5], 0, v[70:71]
	v_cvt_pk_bf16_f32 v6, v6, v7
	v_cvt_pk_bf16_f32 v7, v8, v9
	ds_write_b64 v186, v[6:7]
	v_pk_mul_f32 v[6:7], v[32:33], v[12:13]
	s_waitcnt vmcnt(7)
	v_lshlrev_b32_e32 v8, 16, v86
	v_and_b32_e32 v9, 0xffff0000, v86
	v_pk_mul_f32 v[6:7], v[6:7], v[8:9]
	v_pk_mul_f32 v[8:9], v[32:33], v[14:15]
	v_lshlrev_b32_e32 v10, 16, v87
	v_and_b32_e32 v11, 0xffff0000, v87
	v_pk_mul_f32 v[8:9], v[8:9], v[10:11]
	v_cvt_pk_bf16_f32 v6, v6, v7
	v_cvt_pk_bf16_f32 v7, v8, v9
	ds_write_b64 v186, v[6:7] offset:32
	v_pk_mul_f32 v[6:7], v[32:33], v[16:17]
	s_waitcnt vmcnt(7)
	v_lshlrev_b32_e32 v8, 16, v84
	v_and_b32_e32 v9, 0xffff0000, v84
	v_pk_mul_f32 v[6:7], v[6:7], v[8:9]
	v_pk_mul_f32 v[8:9], v[32:33], v[18:19]
	v_lshlrev_b32_e32 v10, 16, v85
	v_and_b32_e32 v11, 0xffff0000, v85
	v_pk_mul_f32 v[8:9], v[8:9], v[10:11]
	v_cvt_pk_bf16_f32 v6, v6, v7
	v_cvt_pk_bf16_f32 v7, v8, v9
	ds_write_b64 v186, v[6:7] offset:64
	v_pk_mul_f32 v[6:7], v[32:33], v[20:21]
	s_waitcnt vmcnt(7)
	v_lshlrev_b32_e32 v8, 16, v82
	v_and_b32_e32 v9, 0xffff0000, v82
	v_pk_mul_f32 v[6:7], v[6:7], v[8:9]
	v_pk_mul_f32 v[8:9], v[32:33], v[22:23]
	v_lshlrev_b32_e32 v10, 16, v83
	v_and_b32_e32 v11, 0xffff0000, v83
	v_pk_mul_f32 v[8:9], v[8:9], v[10:11]
	v_cvt_pk_bf16_f32 v6, v6, v7
	v_cvt_pk_bf16_f32 v7, v8, v9
	ds_write_b64 v186, v[6:7] offset:96
	v_pk_mul_f32 v[6:7], v[32:33], v[24:25]
	s_waitcnt vmcnt(7)
	v_lshlrev_b32_e32 v8, 16, v80
	v_and_b32_e32 v9, 0xffff0000, v80
	v_pk_mul_f32 v[6:7], v[6:7], v[8:9]
	v_pk_mul_f32 v[8:9], v[32:33], v[26:27]
	v_lshlrev_b32_e32 v10, 16, v81
	v_and_b32_e32 v11, 0xffff0000, v81
	v_pk_mul_f32 v[8:9], v[8:9], v[10:11]
	v_cvt_pk_bf16_f32 v6, v6, v7
	v_cvt_pk_bf16_f32 v7, v8, v9
	ds_write_b64 v186, v[6:7] offset:128
	v_pk_mul_f32 v[6:7], v[32:33], v[28:29]
	s_waitcnt vmcnt(7)
	v_lshlrev_b32_e32 v8, 16, v78
	v_and_b32_e32 v9, 0xffff0000, v78
	v_pk_mul_f32 v[6:7], v[6:7], v[8:9]
	v_pk_mul_f32 v[8:9], v[32:33], v[30:31]
	v_lshlrev_b32_e32 v10, 16, v79
	v_and_b32_e32 v11, 0xffff0000, v79
	v_pk_mul_f32 v[8:9], v[8:9], v[10:11]
	v_cvt_pk_bf16_f32 v6, v6, v7
	v_cvt_pk_bf16_f32 v7, v8, v9
	ds_write_b64 v186, v[6:7] offset:160
	v_pk_mul_f32 v[6:7], v[32:33], v[102:103]
	s_waitcnt vmcnt(7)
	v_lshlrev_b32_e32 v8, 16, v76
	v_and_b32_e32 v9, 0xffff0000, v76
	v_pk_mul_f32 v[6:7], v[6:7], v[8:9]
	v_pk_mul_f32 v[8:9], v[32:33], v[104:105]
	v_lshlrev_b32_e32 v10, 16, v77
	v_and_b32_e32 v11, 0xffff0000, v77
	v_pk_mul_f32 v[8:9], v[8:9], v[10:11]
	v_cvt_pk_bf16_f32 v6, v6, v7
	v_cvt_pk_bf16_f32 v7, v8, v9
	ds_write_b64 v186, v[6:7] offset:192
	v_pk_mul_f32 v[0:1], v[32:33], v[0:1]
	s_waitcnt vmcnt(7)
	v_lshlrev_b32_e32 v6, 16, v74
	v_and_b32_e32 v7, 0xffff0000, v74
	v_pk_mul_f32 v[0:1], v[0:1], v[6:7]
	v_pk_mul_f32 v[2:3], v[32:33], v[2:3]
	v_lshlrev_b32_e32 v6, 16, v75
	v_and_b32_e32 v7, 0xffff0000, v75
	v_pk_mul_f32 v[2:3], v[2:3], v[6:7]
	s_add_i32 s22, s22, s94
	s_add_i32 s18, s18, s29
	v_cvt_pk_bf16_f32 v0, v0, v1
	v_cvt_pk_bf16_f32 v1, v2, v3
	s_cmpk_gt_i32 s22, 0x3ff
	ds_write_b64 v186, v[0:1] offset:224
	s_nop 0
	v_readfirstlane_b32 s98, v4
	v_readfirstlane_b32 s99, v5
	s_waitcnt lgkmcnt(0)
	ds_read_b128 v[74:77], v185
	ds_read_b128 v[78:81], v185 offset:1152
	ds_read_b128 v[82:85], v185 offset:2304
	ds_read_b128 v[86:89], v185 offset:3456
	s_waitcnt lgkmcnt(3)
	global_store_dwordx4 v197, v[74:77], s[98:99] offset:2048
	s_waitcnt lgkmcnt(2)
	s_add_u32 s98, s98, s101
	s_addc_u32 s99, s99, 0
	global_store_dwordx4 v197, v[78:81], s[98:99] offset:2048
	s_waitcnt lgkmcnt(1)
	s_add_u32 s98, s98, s101
	s_addc_u32 s99, s99, 0
	global_store_dwordx4 v197, v[82:85], s[98:99] offset:2048
	s_waitcnt lgkmcnt(0)
	s_add_u32 s98, s98, s101
	s_addc_u32 s99, s99, 0
	global_store_dwordx4 v197, v[86:89], s[98:99] offset:2048
	s_cmpk_gt_i32 s22, 0x3ff
	s_barrier
	s_cbranch_scc0 .LBB0_117
